# attn64 sample units: the six waves that duplicate rows skip the tile-loop compute
# speedup vs baseline: 1.0047x; 1.0047x over previous
.LBB0_924:
	s_and_b64 s[0:1], s[4:5], s[36:37]
	s_cmp_lg_u64 s[0:1], 0
	s_cselect_b32 s32, 1, 0
	s_lshl_b64 s[0:1], s[6:7], 12
	s_add_u32 s6, s78, s0
	s_addc_u32 s12, s79, s1
	s_lshl_b64 s[0:1], s[18:19], 1
	s_add_u32 s42, s6, s0
	s_addc_u32 s43, s12, s1
	s_add_u32 s54, s52, 0x10000
	s_addc_u32 s55, s53, 0
	s_add_u32 s56, s52, 0x20000
	s_addc_u32 s57, s53, 0
	s_add_u32 s58, s52, 0x30000
	s_addc_u32 s59, s53, 0
	s_add_u32 s60, s52, 0x40000
	s_addc_u32 s61, s53, 0
	s_add_u32 s62, s52, 0x50000
	s_addc_u32 s63, s53, 0
	s_add_i32 s1, s50, 3
	s_and_b32 s6, s1, 0xffff
	s_mul_i32 s6, s6, 0xcccd
	s_lshr_b32 s6, s6, 18
	s_add_i32 s51, s50, -1
	s_mul_i32 s6, s6, 5
	s_sub_i32 s1, s1, s6
	s_mul_i32 s6, s51, 0xcd
	s_bfe_u32 s6, s6, 0x6000a
	s_lshl_b32 s0, s51, 13
	s_mul_i32 s6, s6, 5
	s_and_b32 s0, s0, 0x6000
	s_sub_i32 s6, s51, s6
	s_add_i32 s0, s0, 0
	s_and_b32 s1, s1, 0xffff
	s_and_b32 s6, s6, 0xff
	s_lshl_b32 s33, s51, 6
	s_add_i32 s0, s0, 0x14000
	s_lshl_b32 s1, s1, 14
	s_lshl_b32 s34, s6, 14
	s_mov_b64 s[18:19], 0
	s_mov_b64 s[64:65], -1
	v_mov_b32_e32 v186, s10
	v_mov_b32_e32 v187, s11
	s_branch .LBB0_926

.LBB0_938:
	s_cmp_lg_u32 s32, 0
	s_cbranch_scc1 .Latt64_skip_h1
	s_add_i32 s6, s10, 64
	s_cmpk_gt_i32 s6, 0xff41
	s_cselect_b64 s[68:69], -1, 0
	s_cmpk_lt_i32 s6, 0xff42
	s_cselect_b64 vcc, -1, 0
	v_cndmask_b32_e32 v3, 0, v192, vcc
	v_sub_f32_e32 v132, v3, v205
	v_cmp_neq_f32_e32 vcc, v132, v98
	s_cbranch_vccz .LBB0_940
	v_mov_b32_e32 v133, v132
	v_mov_b32_e32 v134, v132
	v_mov_b32_e32 v135, v132
	v_mov_b32_e32 v136, v132
	v_mov_b32_e32 v137, v132
	v_mov_b32_e32 v138, v132
	v_mov_b32_e32 v139, v132
	v_mov_b32_e32 v140, v132
	v_mov_b32_e32 v141, v132
	v_mov_b32_e32 v142, v132
	v_mov_b32_e32 v143, v132
	v_mov_b32_e32 v144, v132
	v_mov_b32_e32 v145, v132
	v_mov_b32_e32 v146, v132
	v_mov_b32_e32 v147, v132
	v_mov_b64_e32 v[82:83], v[132:133]
	v_mov_b64_e32 v[84:85], v[134:135]
	v_mov_b64_e32 v[86:87], v[136:137]
	v_mov_b64_e32 v[88:89], v[138:139]
	v_mov_b64_e32 v[90:91], v[140:141]
	v_mov_b64_e32 v[92:93], v[142:143]
	v_mov_b64_e32 v[94:95], v[144:145]
	v_mov_b64_e32 v[96:97], v[146:147]
	v_mov_b32_e32 v98, v132

.LBB0_946:
	s_mul_hi_u32 s6, s81, 0xcccccccd
	s_lshr_b32 s6, s6, 2
	s_mul_i32 s6, s6, 0x14000
	v_subrev_u32_e32 v16, s6, v215
	s_cmp_lg_u32 0, -1
	s_cselect_b32 s6, 0, 0
	v_add_u32_e32 v16, s6, v16
	ds_read_b64_tr_b16 v[116:117], v16 offset:0x1000
	ds_read_b64_tr_b16 v[118:119], v16 offset:0x1800
	ds_read_b64_tr_b16 v[120:121], v16 offset:0x1200
	ds_read_b64_tr_b16 v[122:123], v16 offset:0x1a00
	ds_read_b64_tr_b16 v[124:125], v16 offset:0x1400
	ds_read_b64_tr_b16 v[126:127], v16 offset:0x1c00
	ds_read_b64_tr_b16 v[128:129], v16 offset:0x1600
	ds_read_b64_tr_b16 v[130:131], v16 offset:0x1e00
	s_waitcnt lgkmcnt(8)
	s_nop 0
	v_mfma_f32_32x32x16_bf16 v[66:81], v[228:231], v[180:183], v[66:81]
	v_exp_f32_e32 v132, v132
	v_exp_f32_e32 v133, v133
	v_mfma_f32_32x32x16_bf16 v[50:65], v[232:235], v[180:183], v[50:65]
	v_exp_f32_e32 v134, v134
	v_exp_f32_e32 v135, v135
	v_mfma_f32_32x32x16_bf16 v[34:49], v[236:239], v[180:183], v[34:49]
	v_exp_f32_e32 v136, v136
	v_exp_f32_e32 v137, v137
	v_mfma_f32_32x32x16_bf16 v[18:33], v[240:243], v[180:183], v[18:33]
	v_exp_f32_e32 v138, v138
	v_exp_f32_e32 v139, v139
	ds_read_b64_tr_b16 v[100:101], v16 offset:0x2000
	ds_read_b64_tr_b16 v[102:103], v16 offset:0x2800
	ds_read_b64_tr_b16 v[104:105], v16 offset:0x2200
	ds_read_b64_tr_b16 v[106:107], v16 offset:0x2a00
	ds_read_b64_tr_b16 v[108:109], v16 offset:0x2400
	ds_read_b64_tr_b16 v[110:111], v16 offset:0x2c00
	ds_read_b64_tr_b16 v[112:113], v16 offset:0x2600
	ds_read_b64_tr_b16 v[114:115], v16 offset:0x2e00
	s_waitcnt lgkmcnt(8)
	v_mfma_f32_32x32x16_bf16 v[66:81], v[116:119], v[12:15], v[66:81]
	v_exp_f32_e32 v140, v140
	v_exp_f32_e32 v141, v141
	v_mfma_f32_32x32x16_bf16 v[50:65], v[120:123], v[12:15], v[50:65]
	v_exp_f32_e32 v142, v142
	v_exp_f32_e32 v143, v143
	v_mfma_f32_32x32x16_bf16 v[34:49], v[124:127], v[12:15], v[34:49]
	v_exp_f32_e32 v144, v144
	v_exp_f32_e32 v145, v145
	v_mfma_f32_32x32x16_bf16 v[18:33], v[128:131], v[12:15], v[18:33]
	v_exp_f32_e32 v146, v146
	v_exp_f32_e32 v147, v147
	ds_read_b64_tr_b16 v[12:13], v16 offset:0x3000
	ds_read_b64_tr_b16 v[14:15], v16 offset:0x3800
	ds_read_b64_tr_b16 v[116:117], v16 offset:0x3200
	ds_read_b64_tr_b16 v[118:119], v16 offset:0x3a00
	ds_read_b64_tr_b16 v[120:121], v16 offset:0x3400
	ds_read_b64_tr_b16 v[122:123], v16 offset:0x3c00
	ds_read_b64_tr_b16 v[124:125], v16 offset:0x3600
	ds_read_b64_tr_b16 v[126:127], v16 offset:0x3e00
	s_waitcnt lgkmcnt(8)
	v_mfma_f32_32x32x16_bf16 v[66:81], v[100:103], v[8:11], v[66:81]
	v_exp_f32_e32 v148, v148
	v_exp_f32_e32 v149, v149
	v_mfma_f32_32x32x16_bf16 v[50:65], v[104:107], v[8:11], v[50:65]
	v_exp_f32_e32 v150, v150
	v_exp_f32_e32 v151, v151
	v_mfma_f32_32x32x16_bf16 v[34:49], v[108:111], v[8:11], v[34:49]
	v_exp_f32_e32 v152, v152
	v_exp_f32_e32 v153, v153
	v_mfma_f32_32x32x16_bf16 v[18:33], v[112:115], v[8:11], v[18:33]
	v_exp_f32_e32 v154, v154
	v_exp_f32_e32 v155, v155
	s_waitcnt lgkmcnt(0)
	v_mfma_f32_32x32x16_bf16 v[66:81], v[12:15], v[4:7], v[66:81]
	v_exp_f32_e32 v156, v156
	v_exp_f32_e32 v157, v157
	v_mfma_f32_32x32x16_bf16 v[50:65], v[116:119], v[4:7], v[50:65]
	v_exp_f32_e32 v158, v158
	v_exp_f32_e32 v159, v159
	v_mfma_f32_32x32x16_bf16 v[34:49], v[120:123], v[4:7], v[34:49]
	v_exp_f32_e32 v160, v160
	v_exp_f32_e32 v161, v161
	v_mfma_f32_32x32x16_bf16 v[18:33], v[124:127], v[4:7], v[18:33]
	v_exp_f32_e32 v162, v162
	v_exp_f32_e32 v163, v163
.Latt64_skip_h1:
	s_add_i32 s83, s84, 2
	s_cmp_ge_u32 s83, s50
	s_cselect_b64 s[68:69], -1, 0
	s_and_b64 vcc, exec, s[68:69]
	s_cbranch_vccnz .LBB0_948
	s_mul_hi_u32 s6, s13, 0xcccccccd
	s_lshr_b32 s6, s6, 2
	s_mul_i32 s6, s6, 0x14000
	s_sub_i32 s17, s14, s6
	s_min_i32 s6, s83, s49
	s_lshl_b64 s[18:19], s[6:7], 17
	s_add_u32 s20, s52, s18
	s_addc_u32 s21, s53, s19
	s_add_u32 s18, s66, s18
	s_addc_u32 s19, s67, s19
	s_cmp_lg_u32 0, -1
	s_cselect_b32 s6, 0, 0
	s_add_i32 s6, s17, s6
	s_add_i32 s17, s80, 0x4000
	s_and_b32 s17, s17, 0x6000
	s_add_i32 s17, s17, s11
	s_mov_b32 s22, m0
	s_mov_b32 m0, s6
	s_nop 0
	global_load_lds_dwordx4 v194, s[20:21]
	s_mov_b32 m0, s22
	s_add_u32 s20, s20, 0x10000
	s_addc_u32 s21, s21, 0
	s_addk_i32 s6, 0x2000
	s_mov_b32 s22, m0
	s_mov_b32 m0, s6
	s_nop 0
	global_load_lds_dwordx4 v194, s[20:21]
	s_mov_b32 m0, s22
	s_mov_b32 s6, m0
	s_mov_b32 m0, s17
	s_nop 0
	global_load_lds_dwordx4 v195, s[18:19]
	s_mov_b32 m0, s6
.LBB0_948:
	s_add_i32 s6, s10, 0x80
	s_cmp_lg_u32 s32, 0
	s_cbranch_scc1 .Latt64_skip_h2
	s_cmpk_gt_i32 s6, 0xff41
	s_cselect_b64 s[70:71], -1, 0
	s_cmpk_lt_i32 s6, 0xff42
	s_cselect_b64 vcc, -1, 0
	v_cndmask_b32_e32 v4, 0, v192, vcc
	v_sub_f32_e32 v100, v4, v205
	v_cmp_neq_f32_e32 vcc, v100, v98
	s_cbranch_vccz .LBB0_950
	v_mov_b32_e32 v101, v100
	v_mov_b32_e32 v102, v100
	v_mov_b32_e32 v103, v100
	v_mov_b32_e32 v104, v100
	v_mov_b32_e32 v105, v100
	v_mov_b32_e32 v106, v100
	v_mov_b32_e32 v107, v100
	v_mov_b32_e32 v108, v100
	v_mov_b32_e32 v109, v100
	v_mov_b32_e32 v110, v100
	v_mov_b32_e32 v111, v100
	v_mov_b32_e32 v112, v100
	v_mov_b32_e32 v113, v100
	v_mov_b32_e32 v114, v100
	v_mov_b32_e32 v115, v100
	v_mov_b64_e32 v[82:83], v[100:101]
	v_mov_b64_e32 v[84:85], v[102:103]
	v_mov_b64_e32 v[86:87], v[104:105]
	v_mov_b64_e32 v[88:89], v[106:107]
	v_mov_b64_e32 v[90:91], v[108:109]
	v_mov_b64_e32 v[92:93], v[110:111]
	v_mov_b64_e32 v[94:95], v[112:113]
	v_mov_b64_e32 v[96:97], v[114:115]
	v_mov_b32_e32 v98, v100

.Latt64_skip_h2:
	s_waitcnt vmcnt(0) lgkmcnt(0)
	s_barrier
	s_addk_i32 s80, 0x4000
	v_add_u32_e32 v214, 0x8000, v214
	s_add_i32 s92, s92, 2
	s_add_i32 s14, s14, 0x8000
	s_add_i32 s13, s13, 2
	v_add_u32_e32 v215, 0x8000, v215
	s_add_i32 s81, s81, 2
	s_add_i32 s15, s15, 0x8000
	s_add_i32 s12, s12, 2
	s_and_b64 vcc, exec, s[68:69]
	s_cbranch_vccnz .LBB0_962
	s_mov_b32 s10, s6
	s_mov_b32 s84, s83
	s_add_i32 s6, s84, 1
	s_cmp_ge_u32 s6, s50
	s_cbranch_scc0 .LBB0_937
	s_branch .LBB0_938
